# plus QKV V-tile bias folded into accumulator init; first grid barrier reads the 16 XCD counters with one wait
# baseline (speedup 1.0000x reference)
.LBB0_1224:
	v_readlane_b32 s24, v236, 27
	v_readlane_b32 s25, v236, 28
	v_readlane_b32 s26, v235, 39
	s_waitcnt lgkmcnt(0)
	s_nop 2
	global_load_dword v0, v3, s[24:25] sc1
	v_readlane_b32 s24, v236, 29
	v_readlane_b32 s25, v236, 30
	s_nop 4
	global_load_dword v1, v3, s[24:25] sc1
	v_readlane_b32 s24, v236, 31
	v_readlane_b32 s25, v236, 32
	s_nop 4
	global_load_dword v2, v3, s[24:25] sc1
	v_readlane_b32 s24, v236, 33
	v_readlane_b32 s25, v236, 34
	s_nop 4
	global_load_dword v4, v3, s[24:25] sc1
	v_readlane_b32 s24, v236, 35
	v_readlane_b32 s25, v236, 36
	s_nop 4
	global_load_dword v5, v3, s[24:25] sc1
	v_readlane_b32 s24, v236, 37
	v_readlane_b32 s25, v236, 38
	s_nop 4
	global_load_dword v6, v3, s[24:25] sc1
	v_readlane_b32 s24, v236, 39
	v_readlane_b32 s25, v236, 40
	s_nop 4
	global_load_dword v7, v3, s[24:25] sc1
	v_readlane_b32 s24, v236, 41
	v_readlane_b32 s25, v236, 42
	s_nop 4
	global_load_dword v8, v3, s[24:25] sc1
	v_readlane_b32 s24, v236, 43
	v_readlane_b32 s25, v236, 44
	s_nop 4
	global_load_dword v9, v3, s[24:25] sc1
	v_readlane_b32 s24, v236, 45
	v_readlane_b32 s25, v236, 46
	s_nop 4
	global_load_dword v10, v3, s[24:25] sc1
	v_readlane_b32 s24, v236, 47
	v_readlane_b32 s25, v236, 48
	s_nop 4
	global_load_dword v11, v3, s[24:25] sc1
	v_readlane_b32 s24, v236, 49
	v_readlane_b32 s25, v236, 50
	s_nop 4
	global_load_dword v12, v3, s[24:25] sc1
	v_readlane_b32 s24, v236, 51
	v_readlane_b32 s25, v236, 52
	s_nop 4
	global_load_dword v13, v3, s[24:25] sc1
	v_readlane_b32 s24, v236, 53
	v_readlane_b32 s25, v236, 54
	s_nop 4
	global_load_dword v14, v3, s[24:25] sc1
	v_readlane_b32 s24, v236, 55
	v_readlane_b32 s25, v236, 56
	s_nop 4
	global_load_dword v15, v3, s[24:25] sc1
	v_readlane_b32 s24, v236, 57
	v_readlane_b32 s25, v236, 58
	s_nop 4
	global_load_dword v16, v3, s[24:25] sc1
	s_mov_b64 s[24:25], -1
	s_waitcnt vmcnt(0)
	v_add_u32_e32 v17, v1, v0
	v_add_u32_e32 v17, v17, v2
	v_add_u32_e32 v17, v17, v4
	v_add_u32_e32 v17, v17, v5
	v_add_u32_e32 v17, v17, v6
	v_add_u32_e32 v17, v17, v7
	v_add_u32_e32 v17, v17, v8
	v_add_u32_e32 v17, v17, v9
	v_add_u32_e32 v17, v17, v10
	v_add_u32_e32 v17, v17, v11
	v_add_u32_e32 v17, v17, v12
	v_add_u32_e32 v17, v17, v13
	v_add_u32_e32 v17, v17, v14
	v_add_u32_e32 v17, v17, v15
	v_add_u32_e32 v17, v17, v16
	v_cmp_eq_u32_e32 vcc, s26, v17
	s_mov_b64 s[26:27], -1
	s_cbranch_vccnz .LBB0_1223
	s_and_b32 s24, s30, 0xff
	s_cmp_eq_u32 s24, 0
	s_mov_b64 s[24:25], -1
	s_mov_b64 s[28:29], -1
	s_sleep 1
	s_cbranch_scc1 .LBB0_1228
	s_and_b64 vcc, exec, s[28:29]
	s_cbranch_vccz .LBB0_1223
